# MLA up-projection GEMMs rebalanced only (WG index rotated by G/2 for k-up and v-up)
# speedup vs baseline: 1.0149x; 1.0014x over previous
.LBB0_770:
	s_mov_b64 s[4:5], s[0:1]
	s_load_dwordx2 s[16:17], s[4:5], 0xe8
	s_mov_b64 s[4:5], s[0:1]
	s_load_dwordx2 s[18:19], s[4:5], 0xe8
	s_lshr_b32 s38, s26, 1
	s_add_i32 s38, s38, s75
	s_sub_i32 s100, s38, s26
	s_cmp_ge_u32 s38, s26
	s_cselect_b32 s38, s100, s38
	s_mov_b64 s[4:5], s[0:1]
	s_load_dwordx2 s[4:5], s[4:5], 0xe8
	v_mov_b32_e32 v8, v224
	s_cmpk_lt_i32 s38, 0x180
	s_cselect_b64 s[20:21], -1, 0
	s_cmpk_gt_i32 s38, 0x17f
	v_readfirstlane_b32 s22, v8
	s_cbranch_scc1 .LBB0_772
	s_ashr_i32 s6, s38, 31
	s_lshr_b32 s6, s6, 29
	s_add_i32 s6, s38, s6
	s_ashr_i32 s7, s6, 3
	s_and_b32 s6, s6, -8
	s_sub_i32 s6, s38, s6
	s_cmp_lt_i32 s6, 0
	s_cselect_b32 s8, 49, 48
	s_mul_i32 s6, s6, s8
	s_add_i32 s6, s6, s7
	s_mul_hi_i32 s7, s6, 0x2aaaaaab
	s_lshr_b32 s8, s7, 31
	s_ashr_i32 s7, s7, 2
	s_add_i32 s7, s7, s8
	s_lshl_b32 s8, s7, 3
	s_mul_i32 s7, s7, 24
	s_sub_i32 s6, s6, s7
	s_bfe_i32 s7, s6, 0x80000
	s_bfe_u32 s7, s7, 0x3000c
	s_add_i32 s7, s6, s7
	s_bfe_i32 s9, s7, 0x80000
	s_and_b32 s7, s7, 0xf8
	s_sub_i32 s6, s6, s7
	s_sext_i32_i16 s9, s9
	s_sext_i32_i8 s6, s6
	s_add_i32 s8, s8, s6
	s_ashr_i32 s6, s9, 3

.LBB0_820:
	s_mov_b64 s[8:9], s[0:1]
	s_mov_b64 s[6:7], s[0:1]
	s_lshr_b32 s24, s26, 1
	s_add_i32 s24, s24, s75
	s_sub_i32 s100, s24, s26
	s_cmp_ge_u32 s24, s26
	s_cselect_b32 s24, s100, s24
	s_mov_b64 s[4:5], s[0:1]
	v_mov_b32_e32 v8, v224
	s_cmpk_gt_i32 s24, 0x17f
	v_readfirstlane_b32 s15, v8
	s_cbranch_scc1 .LBB0_836
	v_lshlrev_b32_e32 v0, 4, v8
	v_add_u32_e32 v1, 0x2000, v0
	v_ashrrev_i32_e32 v2, 31, v1
	v_lshrrev_b32_e32 v2, 22, v2
	v_add_u32_e32 v2, v1, v2
	v_ashrrev_i32_e32 v2, 10, v2
	v_mul_i32_i24_e32 v3, 0x400, v2
	v_sub_u32_e32 v1, v1, v3
	v_lshrrev_b32_e32 v3, 4, v1
	v_bitop3_b32 v1, v3, v1, 32 bitop3:0x6c
	s_load_dwordx2 s[8:9], s[8:9], 0xe8
	v_ashrrev_i32_e32 v3, 31, v1
	v_lshrrev_b32_e32 v3, 26, v3
	v_add_u32_e32 v3, v1, v3
	s_waitcnt vmcnt(0)
	v_lshlrev_b32_e32 v5, 3, v2
	v_ashrrev_i32_e32 v4, 6, v3
	v_and_b32_e32 v5, -16, v5
	s_lshl_b64 s[12:13], s[30:31], 1
	s_load_dwordx2 s[6:7], s[6:7], 0xe8
	v_add_u32_e32 v5, v4, v5
	s_waitcnt lgkmcnt(0)
	s_add_u32 s8, s8, s12
	v_and_b32_e32 v4, 3, v4
	s_mov_b32 s3, 0x1fffe0
	v_lshrrev_b32_e32 v6, 2, v5
	v_lshlrev_b32_e32 v7, 1, v5
	s_addc_u32 s9, s9, s13
	v_and_or_b32 v4, v5, s3, v4
	v_and_b32_e32 v6, 4, v6
	v_and_b32_e32 v7, 24, v7
	v_and_b32_e32 v3, 0xc0, v3
	s_add_u32 s25, s8, 0x2e60000
	v_or3_b32 v4, v4, v6, v7
	v_sub_u32_e32 v1, v1, v3
	v_mov_b32_e32 v7, 1
	s_addc_u32 s38, s9, 0
	v_lshlrev_b32_e32 v2, 5, v2
	v_ashrrev_i16_sdwa v1, v7, sext(v1) dst_sel:DWORD dst_unused:UNUSED_PAD src0_sel:DWORD src1_sel:BYTE_0
	s_add_u32 s39, s6, 0x9200300
	v_and_b32_e32 v2, 32, v2
	v_bfe_i32 v1, v1, 0, 16
	s_addc_u32 s47, s7, 0
	v_add_lshl_u32 v1, v2, v1, 1
	s_ashr_i32 s58, s24, 31
	v_lshl_add_u32 v162, v4, 11, v1
	v_lshl_add_u32 v164, v5, 9, v1
	v_bfe_i32 v1, v8, 27, 1
	s_lshr_b32 s6, s58, 29
	v_lshrrev_b32_e32 v1, 22, v1
	s_add_i32 s6, s24, s6
	s_ashr_i32 s16, s15, 6
	v_add_u32_e32 v1, v0, v1
	s_ashr_i32 s7, s6, 3
	s_and_b32 s6, s6, -8
	s_ashr_i32 s17, s15, 8
	s_lshl_b32 s55, s16, 10
	v_and_b32_e32 v1, 0xfffffc00, v1
	s_sub_i32 s6, s24, s6
	v_sub_u32_e32 v0, v0, v1
	s_cmp_lt_i32 s6, 0
	v_lshrrev_b32_e32 v1, 4, v0
	v_ashrrev_i32_e32 v3, 31, v8
	s_cselect_b32 s8, 49, 48
	v_bitop3_b32 v0, v1, v0, 32 bitop3:0x6c
	v_lshrrev_b32_e32 v3, 26, v3
	s_mul_i32 s6, s6, s8
	v_ashrrev_i32_e32 v1, 31, v0
	v_add_u32_e32 v3, v8, v3
	s_add_i32 s6, s6, s7
	v_lshrrev_b32_e32 v1, 26, v1
	v_ashrrev_i32_e32 v3, 6, v3
	s_ashr_i32 s7, s6, 31
	v_add_u32_e32 v1, v0, v1
	v_lshlrev_b32_e32 v4, 3, v3
	s_lshr_b32 s7, s7, 22
	v_ashrrev_i32_e32 v2, 6, v1
	v_and_b32_e32 v4, -16, v4
	v_and_b32_e32 v1, 0xc0, v1
	s_add_i32 s7, s6, s7
	v_add_u32_e32 v4, v2, v4
	v_sub_u32_e32 v0, v0, v1
	s_ashr_i32 s8, s7, 10
	v_and_b32_e32 v2, 3, v2
	v_lshrrev_b32_e32 v5, 2, v4
	v_lshlrev_b32_e32 v6, 1, v4
	v_lshlrev_b32_e32 v3, 5, v3
	v_ashrrev_i16_sdwa v0, v7, sext(v0) dst_sel:DWORD dst_unused:UNUSED_PAD src0_sel:DWORD src1_sel:BYTE_0
	s_lshl_b32 s8, s8, 3
	v_and_or_b32 v2, v4, s3, v2
	v_and_b32_e32 v5, 4, v5
	v_and_b32_e32 v6, 24, v6
	v_and_b32_e32 v3, 32, v3
	v_bfe_i32 v0, v0, 0, 16
	s_sub_i32 s9, 3, s8
	v_or3_b32 v2, v2, v5, v6
	v_add_lshl_u32 v0, v3, v0, 1
	s_min_u32 s9, s9, 8
	s_and_b32 s7, s7, 0xfffffc00
	v_lshl_add_u32 v166, v2, 11, v0
	s_sub_i32 s12, s6, s7
	v_cvt_f32_ubyte0_e32 v2, s9
	v_cvt_f32_i32_e32 v1, s12
	v_rcp_iflag_f32_e32 v3, v2
	v_lshl_add_u32 v168, v4, 9, v0
	s_ashr_i32 s6, s12, 30
	s_or_b32 s13, s6, 1
	v_mul_f32_e32 v0, v1, v3
	v_trunc_f32_e32 v0, v0
	v_fma_f32 v1, -v0, v2, v1
	v_cvt_i32_f32_e32 v0, v0
	v_cmp_ge_f32_e64 s[6:7], |v1|, v2
	s_and_b64 s[6:7], s[6:7], exec
	s_cselect_b32 s6, s13, 0
	v_readfirstlane_b32 s7, v0
	s_add_i32 s14, s7, s6
	s_mul_i32 s6, s14, s9
	s_sub_i32 s6, s12, s6
	s_sext_i32_i16 s6, s6
	s_add_i32 s6, s8, s6
	s_ashr_i32 s7, s6, 31
	s_bfe_i64 s[12:13], s[14:15], 0x100000
	s_lshl_b64 s[8:9], s[6:7], 17
	s_lshl_b64 s[12:13], s[12:13], 19
	s_add_u32 s30, s39, s12
	s_addc_u32 s31, s47, s13
	s_add_i32 s56, s55, 0
	s_add_i32 m0, s56, 0x10000
	s_load_dwordx2 s[4:5], s[4:5], 0xe8
	global_load_lds_dwordx4 v166, s[30:31]
	s_add_i32 m0, s56, 0x12000
	s_add_u32 s12, s30, 0x40000
	global_load_lds_dwordx4 v162, s[30:31]
	s_addc_u32 s13, s31, 0
	s_add_i32 m0, s56, 0x14000
	v_mov_b32_e32 v167, v113
	global_load_lds_dwordx4 v166, s[12:13]
	s_add_i32 m0, s56, 0x16000
	s_add_u32 s34, s25, s8
	s_addc_u32 s35, s38, s9
	s_add_i32 s69, s56, 0x2000
	global_load_lds_dwordx4 v162, s[12:13]
	s_mov_b32 m0, s56
	s_add_u32 s8, s34, 0x10000
	global_load_lds_dwordx4 v168, s[34:35]
	s_mov_b32 m0, s69
	s_addc_u32 s9, s35, 0
	s_add_i32 s70, s56, 0x4000
	global_load_lds_dwordx4 v164, s[34:35]
	s_mov_b32 m0, s70
	s_add_i32 s71, s56, 0x6000
	global_load_lds_dwordx4 v168, s[8:9]
	s_mov_b32 m0, s71
	v_mov_b32_e32 v163, v113
	global_load_lds_dwordx4 v164, s[8:9]
	v_mov_b32_e32 v169, v113
	v_mov_b32_e32 v165, v113
	s_cmp_eq_u32 s17, 1
	v_lshl_add_u64 v[6:7], s[30:31], 0, v[166:167]
	v_lshl_add_u64 v[4:5], s[30:31], 0, v[162:163]
	v_lshl_add_u64 v[0:1], s[34:35], 0, v[168:169]
	s_cselect_b64 s[8:9], -1, 0
	s_cmp_lg_u32 s17, 1
	v_lshl_add_u64 v[2:3], s[34:35], 0, v[164:165]
	s_cbranch_scc1 .LBB0_823
	s_barrier

	.amdhsa_kernel _Z8mega_fwd6Params
		.amdhsa_group_segment_fixed_size 0
		.amdhsa_private_segment_fixed_size 0
		.amdhsa_kernarg_size 496
		.amdhsa_user_sgpr_count 2
		.amdhsa_user_sgpr_dispatch_ptr 0
		.amdhsa_user_sgpr_queue_ptr 0
		.amdhsa_user_sgpr_kernarg_segment_ptr 1
		.amdhsa_user_sgpr_dispatch_id 0
		.amdhsa_user_sgpr_kernarg_preload_length 0
		.amdhsa_user_sgpr_kernarg_preload_offset 0
		.amdhsa_user_sgpr_private_segment_size 0
		.amdhsa_uses_dynamic_stack 0
		.amdhsa_enable_private_segment 0
		.amdhsa_system_sgpr_workgroup_id_x 1
		.amdhsa_system_sgpr_workgroup_id_y 0
		.amdhsa_system_sgpr_workgroup_id_z 0
		.amdhsa_system_sgpr_workgroup_info 0
		.amdhsa_system_vgpr_workitem_id 2
		.amdhsa_next_free_vgpr 256
		.amdhsa_next_free_sgpr 102
		.amdhsa_accum_offset 256
		.amdhsa_reserve_vcc 1
		.amdhsa_float_round_mode_32 0
		.amdhsa_float_round_mode_16_64 0
		.amdhsa_float_denorm_mode_32 3
		.amdhsa_float_denorm_mode_16_64 3
		.amdhsa_dx10_clamp 1
		.amdhsa_ieee_mode 1
		.amdhsa_fp16_overflow 0
		.amdhsa_tg_split 0
		.amdhsa_exception_fp_ieee_invalid_op 0
		.amdhsa_exception_fp_denorm_src 0
		.amdhsa_exception_fp_ieee_div_zero 0
		.amdhsa_exception_fp_ieee_overflow 0
		.amdhsa_exception_fp_ieee_underflow 0
		.amdhsa_exception_fp_ieee_inexact 0
		.amdhsa_exception_int_div_zero 0
	.end_amdhsa_kernel

amdhsa.kernels:
  - .agpr_count:     0
    .args:
      - .offset:         0
        .size:           240
        .value_kind:     by_value
      - .offset:         240
        .size:           4
        .value_kind:     hidden_block_count_x
      - .offset:         244
        .size:           4
        .value_kind:     hidden_block_count_y
      - .offset:         248
        .size:           4
        .value_kind:     hidden_block_count_z
      - .offset:         252
        .size:           2
        .value_kind:     hidden_group_size_x
      - .offset:         254
        .size:           2
        .value_kind:     hidden_group_size_y
      - .offset:         256
        .size:           2
        .value_kind:     hidden_group_size_z
      - .offset:         258
        .size:           2
        .value_kind:     hidden_remainder_x
      - .offset:         260
        .size:           2
        .value_kind:     hidden_remainder_y
      - .offset:         262
        .size:           2
        .value_kind:     hidden_remainder_z
      - .offset:         280
        .size:           8
        .value_kind:     hidden_global_offset_x
      - .offset:         288
        .size:           8
        .value_kind:     hidden_global_offset_y
      - .offset:         296
        .size:           8
        .value_kind:     hidden_global_offset_z
      - .offset:         304
        .size:           2
        .value_kind:     hidden_grid_dims
      - .offset:         328
        .size:           8
        .value_kind:     hidden_multigrid_sync_arg
      - .offset:         360
        .size:           4
        .value_kind:     hidden_dynamic_lds_size
    .group_segment_fixed_size: 0
    .kernarg_segment_align: 8
    .kernarg_segment_size: 496
    .language:       OpenCL C
    .language_version:
      - 2
      - 0
    .max_flat_workgroup_size: 512
    .name:           _Z8mega_fwd6Params
    .private_segment_fixed_size: 0
    .sgpr_count:     108
    .sgpr_spill_count: 57
    .symbol:         _Z8mega_fwd6Params.kd
    .uniform_work_group_size: 1
    .uses_dynamic_stack: false
    .vgpr_count:     256
    .vgpr_spill_count: 0
    .wavefront_size: 64
